# v75 + A2 k-rows: gcs/beta via per-unit LDS vector read and v_readlane instead of two blocking uniform ds_reads per row; nt policy on the write-once swiglu HID stores and the GLA scan output stores
# speedup vs baseline: 1.0176x; 1.0128x over previous
; __device__ __forceinline__ unsigned f2bf(float f) { unsigned u = __float_as_uint(f); return (u + 0x7fffu + ((u >> 16) & 1u)) >> 16; }
; __device__ __forceinline__ void gdn_local_unit(const Ctx& F, int hv, int n) {
;     ...
;     {
;         const int which = w >> 2; const float gl = gcs[63];
;         for (int rr = 0; rr < 16; ++rr) {
;             const int t = (w & 3) * 16 + rr; const float a = tmp[(which * 64 + t) * 129 + lane], b = tmp[(which * 64 + t) * 129 + lane + 64];
;             const float ss = wave_sum(a * a + b * b); float rinv = rsqrtf(ss + EPS);
;             if (which == 0) { rinv *= 0.08838834764831845f; qn[t * 136 + lane] = (bf16_t)f2bf(a * rinv); qn[t * 136 + lane + 64] = (bf16_t)f2bf(b * rinv); }
;             else { const float ka = a * rinv, kb = b * rinv, gt = gcs[t]; const float e1 = bts[t] * __expf(gt), e2 = __expf(gl - gt);
;                 kn[t * 136 + lane] = (bf16_t)f2bf(ka); kn[t * 136 + lane + 64] = (bf16_t)f2bf(kb);
;                 kbgT[lane * 72 + t] = (bf16_t)f2bf(ka * e1); kbgT[(lane + 64) * 72 + t] = (bf16_t)f2bf(kb * e1);
;                 kdT[lane * 72 + t] = (bf16_t)f2bf(ka * e2); kdT[(lane + 64) * 72 + t] = (bf16_t)f2bf(kb * e2); }
.LBB0_649:
	s_or_b64 exec, exec, s[24:25]
	s_waitcnt lgkmcnt(0)
	s_barrier
	v_mbcnt_lo_u32_b32 v234, -1, 0
	v_mbcnt_hi_u32_b32 v234, -1, v234
	v_lshlrev_b32_e32 v234, 2, v234
	v_add_u32_e32 v235, 0x27900, v234
	v_add_u32_e32 v234, 0x27800, v234
	ds_read_b32 v234, v234
	ds_read_b32 v235, v235
	v_mov_b32_e32 v0, s19
	ds_read_b32 v2, v0
	v_and_b32_e32 v0, 64, v81
	v_add_u32_e32 v0, 64, v0
	v_xor_b32_e32 v1, 1, v81
	v_cmp_lt_i32_e32 vcc, v1, v0
	s_mov_b32 s12, 16
	s_mov_b32 s13, s17
	v_cndmask_b32_e32 v1, v81, v1, vcc
	v_lshlrev_b32_e32 v3, 2, v1
	v_xor_b32_e32 v1, 2, v81
	v_cmp_lt_i32_e32 vcc, v1, v0
	v_mov_b32_e32 v15, v75
	v_mov_b32_e32 v16, v74
	v_cndmask_b32_e32 v1, v81, v1, vcc
	v_lshlrev_b32_e32 v8, 2, v1
	v_xor_b32_e32 v1, 4, v81
	v_cmp_lt_i32_e32 vcc, v1, v0
	v_mov_b32_e32 v17, v73
	s_nop 0
	v_cndmask_b32_e32 v1, v81, v1, vcc
	v_lshlrev_b32_e32 v11, 2, v1
	v_xor_b32_e32 v1, 8, v81
	v_cmp_lt_i32_e32 vcc, v1, v0
	s_nop 1
	v_cndmask_b32_e32 v1, v81, v1, vcc
	v_lshlrev_b32_e32 v12, 2, v1
	v_xor_b32_e32 v1, 16, v81
	v_cmp_lt_i32_e32 vcc, v1, v0
	s_nop 1
	v_cndmask_b32_e32 v1, v81, v1, vcc
	v_lshlrev_b32_e32 v13, 2, v1
	v_xor_b32_e32 v1, 32, v81
	v_cmp_lt_i32_e32 vcc, v1, v0
	s_nop 1
	v_cndmask_b32_e32 v0, v81, v1, vcc
	v_lshlrev_b32_e32 v14, 2, v0
	s_branch .LBB0_651

; __device__ __forceinline__ unsigned f2bf(float f) { unsigned u = __float_as_uint(f); return (u + 0x7fffu + ((u >> 16) & 1u)) >> 16; }
; __device__ __forceinline__ void gdn_local_unit(const Ctx& F, int hv, int n) {
;     ...
;         for (int rr = 0; rr < 16; ++rr) {
;             const int t = (w & 3) * 16 + rr; const float a = tmp[(which * 64 + t) * 129 + lane], b = tmp[(which * 64 + t) * 129 + lane + 64];
;             const float ss = wave_sum(a * a + b * b); float rinv = rsqrtf(ss + EPS);
;             if (which == 0) { rinv *= 0.08838834764831845f; qn[t * 136 + lane] = (bf16_t)f2bf(a * rinv); qn[t * 136 + lane + 64] = (bf16_t)f2bf(b * rinv); }
;             else { const float ka = a * rinv, kb = b * rinv, gt = gcs[t]; const float e1 = bts[t] * __expf(gt), e2 = __expf(gl - gt);
;                 kn[t * 136 + lane] = (bf16_t)f2bf(ka); kn[t * 136 + lane + 64] = (bf16_t)f2bf(kb);
;                 kbgT[lane * 72 + t] = (bf16_t)f2bf(ka * e1); kbgT[(lane + 64) * 72 + t] = (bf16_t)f2bf(kb * e1);
;                 kdT[lane * 72 + t] = (bf16_t)f2bf(ka * e2); kdT[(lane + 64) * 72 + t] = (bf16_t)f2bf(kb * e2); }
.LBB0_651:
	v_add_u32_e32 v0, 0, v15
	ds_read2st64_b32 v[0:1], v0 offset1:1
	s_mov_b32 s4, 0x800000
	s_and_b64 s[24:25], exec, s[62:63]
	s_waitcnt lgkmcnt(0)
	v_pk_mul_f32 v[98:99], v[0:1], v[0:1]
	s_nop 0
	v_add_f32_e32 v98, v98, v99
	s_nop 1
	v_add_f32_dpp v98, v98, v98 quad_perm:[1,0,3,2] row_mask:0xf bank_mask:0xf
	s_nop 1
	v_add_f32_dpp v98, v98, v98 quad_perm:[2,3,0,1] row_mask:0xf bank_mask:0xf
	s_nop 1
	v_add_f32_dpp v98, v98, v98 row_half_mirror row_mask:0xf bank_mask:0xf
	s_nop 1
	v_add_f32_dpp v98, v98, v98 row_mirror row_mask:0xf bank_mask:0xf
	s_nop 1
	v_readlane_b32 s5, v98, 0
	v_readlane_b32 vcc_lo, v98, 16
	v_readlane_b32 vcc_hi, v98, 32
	s_nop 1
	v_mov_b32_e32 v99, s5
	v_add_f32_e32 v99, vcc_lo, v99
	v_readlane_b32 s5, v98, 48
	v_add_f32_e32 v99, vcc_hi, v99
	s_nop 1
	v_add_f32_e32 v98, s5, v99
	v_add_f32_e32 v98, 0x358637bd, v98
	v_mul_f32_e32 v99, 0x4b800000, v98
	v_cmp_gt_f32_e32 vcc, s4, v98
	s_mov_b64 s[4:5], -1
	s_nop 0
	v_cndmask_b32_e32 v98, v98, v99, vcc
	v_rsq_f32_e32 v99, v98
	v_add_u32_e32 v98, 0, v17
	v_mul_f32_e32 v100, 0x45800000, v99
	v_cndmask_b32_e32 v99, v99, v100, vcc
	s_mov_b64 vcc, s[24:25]
	s_cbranch_vccz .LBB0_653
	s_lshr_b32 vcc_lo, s13, 2
	v_readlane_b32 s5, v234, vcc_lo
	v_readlane_b32 s4, v235, vcc_lo
	v_mul_f32_e32 v101, v0, v99
	s_nop 0
	v_mov_b32_e32 v100, s5
	v_mov_b32_e32 v102, s4
	v_mul_f32_e32 v103, 0x3fb8aa3b, v100
	v_exp_f32_e32 v103, v103
	v_mul_f32_e32 v104, v1, v99
	v_add_u32_e32 v105, 0x15c00, v98
	v_sub_f32_e32 v100, v2, v100
	v_mul_f32_e32 v102, v102, v103
	v_bfe_u32 v103, v101, 16, 1
	v_add3_u32 v103, v101, v103, s18
	ds_write_b16_d16_hi v105, v103
	v_bfe_u32 v103, v104, 16, 1
	v_add3_u32 v103, v104, v103, s18
	v_add_u32_e32 v105, 0x15c80, v98
	v_mul_f32_e32 v100, 0x3fb8aa3b, v100
	ds_write_b16_d16_hi v105, v103
	v_mul_f32_e32 v103, v101, v102
	v_exp_f32_e32 v100, v100
	v_bfe_u32 v105, v103, 16, 1
	v_add3_u32 v103, v103, v105, s18
	v_add_u32_e32 v105, 0, v16
	v_add_u32_e32 v106, 0x1e800, v105
	v_mul_f32_e32 v102, v104, v102
	ds_write_b16_d16_hi v106, v103
	v_bfe_u32 v103, v102, 16, 1
	v_add3_u32 v102, v102, v103, s18
	v_add_u32_e32 v103, 0x20c00, v105
	v_mul_f32_e32 v101, v101, v100
	ds_write_b16_d16_hi v103, v102
	v_bfe_u32 v102, v101, 16, 1
	v_add3_u32 v101, v101, v102, s18
	v_add_u32_e32 v102, 0x23000, v105
	v_mul_f32_e32 v100, v104, v100
	ds_write_b16_d16_hi v102, v101
	v_bfe_u32 v101, v100, 16, 1
	v_add3_u32 v100, v100, v101, s18
	v_add_u32_e32 v101, 0x25400, v105
	ds_write_b16_d16_hi v101, v100
	s_mov_b64 s[4:5], 0

; #define LAS __attribute__((address_space(3)))
; __device__ __forceinline__ unsigned pk2(float lo, float hi) { return f2bf(lo) | (f2bf(hi) << 16); }
; __device__ __forceinline__ f32x4 mfma16(bf16x8 a, bf16x8 b, f32x4 c) { return __builtin_amdgcn_mfma_f32_16x16x32_bf16(a, b, c, 0, 0, 0); }
; __device__ __forceinline__ void gla_scan_wg(const Ctx& F, int h, int sl) {
;     ...
;                 { const int nn = (n + 2 < 256) ? n + 2 : 255; ls_load(ring[(j + 2) % 3], QT, KDTb, ATTb, VTb, GLAST, h, nn, w, fr, fq, dv0, dk0); }
;                 const LS& x = ring[j % 3];
;                 if (publish && tid == 0) __hip_atomic_store(prog, n, __ATOMIC_RELAXED, __HIP_MEMORY_SCOPE_AGENT);
;                 u32x4 sp; sp.x = pk2(s0[0], s0[1]); sp.y = pk2(s0[2], s0[3]); sp.z = pk2(s1[0], s1[1]); sp.w = pk2(s1[2], s1[3]);
;                 const bf16x8 sf = __builtin_bit_cast(bf16x8, sp);
;                 f32x4 op[4];
; #pragma unroll
;                 for (int mt = 0; mt < 4; ++mt) op[mt] = mfma16(sf, x.qf[mt], (f32x4){0.f, 0.f, 0.f, 0.f});
;                 if (w < 4) {
;                     f32x4 oi = (f32x4){0.f, 0.f, 0.f, 0.f};
; #pragma unroll
;                     for (int ks = 0; ks < 2; ++ks) oi = mfma16(x.vf[ks], x.af[ks], oi);
; #pragma unroll
;                     for (int mt = 0; mt < 4; ++mt) if (mt == w) op[mt] += oi;
;                 }
; #pragma unroll
;                 for (int mt = 0; mt < 4; ++mt) *(LAS f32x4*)(OP + ((buf * 8 + w) * 64 + mt * 16 + fr) * 16 + fq * 4) = op[mt];
;                 f32x4 u0 = (f32x4){0.f, 0.f, 0.f, 0.f}, u1 = u0;
; #pragma unroll
;                 for (int ks = 0; ks < 2; ++ks) { u0 = mfma16(x.kf[0][ks], x.vf[ks], u0); u1 = mfma16(x.kf[1][ks], x.vf[ks], u1); }
;                 s0 = s0 * x.g0 + u0; s1 = s1 * x.g1 + u1;
;                 asm volatile("s_waitcnt lgkmcnt(0)" ::: "memory"); __builtin_amdgcn_s_barrier(); asm volatile("" ::: "memory");
;                 { const int e = tid * 2; float a = 0.f, b = 0.f;
; #pragma unroll
;                     for (int ww = 0; ww < 8; ++ww) { const f32x2 xx = *(const LAS f32x2*)(OP + (buf * 8 + ww) * 1024 + e); a += xx[0]; b += xx[1]; }
;                     *(unsigned*)(O + ((size_t)(h * 32 + (dv0 >> 4)) * SEQ + t0) * 16 + e) = pk2(a, b); }
.LBB0_1746:
	ds_write_b128 v215, v[116:119]
	ds_write_b128 v215, v[76:79] offset:1024
	s_nop 0
	ds_write_b128 v215, v[32:35] offset:2048
	s_nop 0
	ds_write_b128 v215, v[36:39] offset:3072
	s_waitcnt lgkmcnt(0)
	s_barrier
	s_waitcnt vmcnt(16)
	v_mfma_f32_16x16x32_bf16 v[4:7], v[4:7], v[24:27], 0
	v_lshl_add_u64 v[240:241], s[92:93], 0, v[228:229]
	v_add_co_u32_e32 v164, vcc, s42, v240
	v_mfma_f32_16x16x32_bf16 v[8:11], v[8:11], v[24:27], 0
	ds_read2st64_b64 v[24:27], v213 offset1:8
	v_addc_co_u32_e32 v165, vcc, 0, v241, vcc
	s_waitcnt vmcnt(15)
	v_mfma_f32_16x16x32_bf16 v[120:123], v[0:3], v[28:31], v[4:7]
	ds_read2st64_b64 v[0:3], v213 offset0:16 offset1:24
	s_nop 1
	ds_read2st64_b64 v[4:7], v213 offset0:32 offset1:40
	ds_read2st64_b64 v[32:35], v213 offset0:48 offset1:56
	v_mfma_f32_16x16x32_bf16 v[116:119], v[16:19], v[28:31], v[8:11]
	s_waitcnt lgkmcnt(3)
	s_nop 1
	v_pk_add_f32 v[8:9], v[24:25], 0 op_sel_hi:[1,0]
	s_nop 0
	v_pk_add_f32 v[8:9], v[8:9], v[26:27]
	s_waitcnt lgkmcnt(2)
	v_pk_add_f32 v[0:1], v[8:9], v[0:1]
	s_nop 0
	v_pk_add_f32 v[0:1], v[0:1], v[2:3]
	s_waitcnt lgkmcnt(1)
	v_pk_add_f32 v[0:1], v[0:1], v[4:5]
	s_nop 0
	v_pk_add_f32 v[0:1], v[0:1], v[6:7]
	s_waitcnt lgkmcnt(0)
	v_pk_add_f32 v[0:1], v[0:1], v[32:33]
	s_nop 0
	v_pk_add_f32 v[0:1], v[0:1], v[34:35]
	s_nop 0
	v_and_b32_sdwa v3, v0, v243 dst_sel:DWORD dst_unused:UNUSED_PAD src0_sel:WORD_1 src1_sel:DWORD
	v_and_b32_sdwa v2, v1, v243 dst_sel:DWORD dst_unused:UNUSED_PAD src0_sel:WORD_1 src1_sel:DWORD
	v_add3_u32 v0, v0, v3, s40
	v_add3_u32 v1, v1, v2, s40
	v_lshrrev_b32_e32 v0, 16, v0
	v_and_or_b32 v0, v1, s41, v0
	global_store_dword v[164:165], v0, off nt
	v_add_co_u32_e32 v0, vcc, s43, v156
	s_nop 1
	v_addc_co_u32_e32 v1, vcc, 0, v157, vcc
	v_add_co_u32_e32 v16, vcc, s44, v156
	global_load_dwordx4 v[76:79], v[0:1], off
	global_load_dwordx4 v[32:35], v[0:1], off offset:1024
	global_load_dwordx4 v[36:39], v[0:1], off offset:2048
	global_load_dwordx4 v[48:51], v[0:1], off offset:3072
	v_addc_co_u32_e32 v17, vcc, 0, v157, vcc
	v_add_co_u32_e32 v28, vcc, 0x23430000, v158
	global_load_dwordx4 v[4:7], v[16:17], off
	global_load_dwordx4 v[0:3], v[16:17], off offset:1024
	global_load_dwordx4 v[8:11], v[16:17], off offset:2048
	s_nop 0
	global_load_dwordx4 v[16:19], v[16:17], off offset:3072
	v_addc_co_u32_e32 v29, vcc, 0, v159, vcc
	v_add_co_u32_e32 v160, vcc, 0x603000, v160
	global_load_dwordx4 v[24:27], v[28:29], off
	s_nop 0
	global_load_dwordx4 v[28:31], v[28:29], off offset:1024
	v_addc_co_u32_e32 v161, vcc, 0, v161, vcc
	global_load_dwordx4 v[156:159], v[160:161], off
	s_nop 0
	global_load_dwordx4 v[160:163], v[160:161], off offset:64
	s_and_b64 vcc, exec, s[12:13]
	s_cbranch_vccnz .LBB0_1748
	s_waitcnt vmcnt(27)
	v_add_co_u32_e32 v12, vcc, 0x22c06000, v166
	s_nop 1
	v_addc_co_u32_e32 v13, vcc, 0, v167, vcc
	s_waitcnt vmcnt(26)
	v_add_co_u32_e32 v20, vcc, 0x22c06000, v82
	s_nop 1
	v_addc_co_u32_e32 v21, vcc, 0, v83, vcc
	global_load_dwordx4 v[12:15], v[12:13], off
	s_nop 0
	global_load_dwordx4 v[20:23], v[20:21], off

; #define LAS __attribute__((address_space(3)))
; __device__ __forceinline__ unsigned pk2(float lo, float hi) { return f2bf(lo) | (f2bf(hi) << 16); }
; __device__ __forceinline__ f32x4 mfma16(bf16x8 a, bf16x8 b, f32x4 c) { return __builtin_amdgcn_mfma_f32_16x16x32_bf16(a, b, c, 0, 0, 0); }
; __device__ __forceinline__ void gla_scan_wg(const Ctx& F, int h, int sl) {
;     ...
;                 { const int nn = (n + 2 < 256) ? n + 2 : 255; ls_load(ring[(j + 2) % 3], QT, KDTb, ATTb, VTb, GLAST, h, nn, w, fr, fq, dv0, dk0); }
;                 const LS& x = ring[j % 3];
;                 if (publish && tid == 0) __hip_atomic_store(prog, n, __ATOMIC_RELAXED, __HIP_MEMORY_SCOPE_AGENT);
;                 u32x4 sp; sp.x = pk2(s0[0], s0[1]); sp.y = pk2(s0[2], s0[3]); sp.z = pk2(s1[0], s1[1]); sp.w = pk2(s1[2], s1[3]);
;                 const bf16x8 sf = __builtin_bit_cast(bf16x8, sp);
;                 f32x4 op[4];
; #pragma unroll
;                 for (int mt = 0; mt < 4; ++mt) op[mt] = mfma16(sf, x.qf[mt], (f32x4){0.f, 0.f, 0.f, 0.f});
;                 if (w < 4) {
;                     f32x4 oi = (f32x4){0.f, 0.f, 0.f, 0.f};
; #pragma unroll
;                     for (int ks = 0; ks < 2; ++ks) oi = mfma16(x.vf[ks], x.af[ks], oi);
; #pragma unroll
;                     for (int mt = 0; mt < 4; ++mt) if (mt == w) op[mt] += oi;
;                 }
; #pragma unroll
;                 for (int mt = 0; mt < 4; ++mt) *(LAS f32x4*)(OP + ((buf * 8 + w) * 64 + mt * 16 + fr) * 16 + fq * 4) = op[mt];
;                 f32x4 u0 = (f32x4){0.f, 0.f, 0.f, 0.f}, u1 = u0;
; #pragma unroll
;                 for (int ks = 0; ks < 2; ++ks) { u0 = mfma16(x.kf[0][ks], x.vf[ks], u0); u1 = mfma16(x.kf[1][ks], x.vf[ks], u1); }
;                 s0 = s0 * x.g0 + u0; s1 = s1 * x.g1 + u1;
;                 asm volatile("s_waitcnt lgkmcnt(0)" ::: "memory"); __builtin_amdgcn_s_barrier(); asm volatile("" ::: "memory");
;                 { const int e = tid * 2; float a = 0.f, b = 0.f;
; #pragma unroll
;                     for (int ww = 0; ww < 8; ++ww) { const f32x2 xx = *(const LAS f32x2*)(OP + (buf * 8 + ww) * 1024 + e); a += xx[0]; b += xx[1]; }
;                     *(unsigned*)(O + ((size_t)(h * 32 + (dv0 >> 4)) * SEQ + t0) * 16 + e) = pk2(a, b); }
.LBB0_1754:
	ds_write_b128 v215, v[112:115] offset:32768
	ds_write_b128 v215, v[108:111] offset:33792
	s_nop 0
	ds_write_b128 v215, v[82:85] offset:34816
	s_nop 0
	ds_write_b128 v215, v[86:89] offset:35840
	s_waitcnt lgkmcnt(0)
	s_barrier
	s_waitcnt vmcnt(28)
	v_mfma_f32_16x16x32_bf16 v[44:47], v[44:47], v[72:75], 0
	s_add_i32 s47, s46, 2
	s_min_u32 s14, s47, 0xfd
	s_add_i32 s31, s14, 2
	v_mfma_f32_16x16x32_bf16 v[56:59], v[56:59], v[72:75], 0
	ds_read2st64_b64 v[72:75], v213 offset0:64 offset1:72
	s_add_i32 s30, s31, s35
	s_lshl_b32 s14, s30, 15
	s_waitcnt vmcnt(27)
	v_mfma_f32_16x16x32_bf16 v[112:115], v[40:43], v[68:71], v[44:47]
	ds_read2st64_b64 v[40:43], v213 offset0:80 offset1:88
	s_nop 1
	ds_read2st64_b64 v[44:47], v213 offset0:96 offset1:104
	ds_read2st64_b64 v[82:85], v213 offset0:112 offset1:120
	s_and_b64 vcc, exec, s[12:13]
	v_mfma_f32_16x16x32_bf16 v[108:111], v[52:55], v[68:71], v[56:59]
	s_waitcnt lgkmcnt(3)
	v_pk_add_f32 v[52:53], v[72:73], 0 op_sel_hi:[1,0]
	s_nop 0
	v_pk_add_f32 v[52:53], v[52:53], v[74:75]
	s_waitcnt lgkmcnt(2)
	v_pk_add_f32 v[40:41], v[52:53], v[40:41]
	v_lshl_add_u64 v[52:53], v[224:225], 0, s[14:15]
	v_pk_add_f32 v[40:41], v[40:41], v[42:43]
	s_waitcnt lgkmcnt(1)
	v_pk_add_f32 v[40:41], v[40:41], v[44:45]
	s_nop 0
	v_pk_add_f32 v[40:41], v[40:41], v[46:47]
	s_waitcnt lgkmcnt(0)
	v_pk_add_f32 v[40:41], v[40:41], v[82:83]
	s_nop 0
	v_pk_add_f32 v[40:41], v[40:41], v[84:85]
	s_nop 0
	v_and_b32_sdwa v43, v40, v243 dst_sel:DWORD dst_unused:UNUSED_PAD src0_sel:WORD_1 src1_sel:DWORD
	v_and_b32_sdwa v42, v41, v243 dst_sel:DWORD dst_unused:UNUSED_PAD src0_sel:WORD_1 src1_sel:DWORD
	v_add3_u32 v40, v40, v43, s40
	v_add3_u32 v41, v41, v42, s40
	v_lshrrev_b32_e32 v40, 16, v40
	v_and_or_b32 v40, v41, s41, v40
	global_store_dword v[164:165], v40, off offset:2048 nt
	v_lshl_add_u64 v[40:41], v[222:223], 0, s[14:15]
	s_lshl_b32 s14, s30, 16
	global_load_dwordx4 v[84:87], v[40:41], off
	global_load_dwordx4 v[88:91], v[40:41], off offset:1024
	global_load_dwordx4 v[92:95], v[40:41], off offset:2048
	global_load_dwordx4 v[96:99], v[40:41], off offset:3072
	global_load_dwordx4 v[44:47], v[52:53], off
	s_nop 0
	global_load_dwordx4 v[40:43], v[52:53], off offset:1024
	global_load_dwordx4 v[56:59], v[52:53], off offset:2048
	s_nop 0
	global_load_dwordx4 v[52:55], v[52:53], off offset:3072
	v_lshl_add_u64 v[68:69], v[226:227], 0, s[14:15]
	s_lshl_b32 s14, s31, 12
	v_lshl_add_u64 v[82:83], v[216:217], 0, s[14:15]
	global_load_dwordx4 v[72:75], v[68:69], off
	s_nop 0
	global_load_dwordx4 v[68:71], v[68:69], off offset:1024
	s_nop 0
	global_load_dwordx4 v[116:119], v[82:83], off
	global_load_dwordx4 v[120:123], v[82:83], off offset:64
	s_cbranch_vccnz .LBB0_1756
	s_lshl_b32 s14, s30, 13
	s_add_u32 s30, s3, s14
	s_addc_u32 s31, s34, 0
	s_waitcnt vmcnt(38)
	v_lshl_add_u64 v[64:65], v[220:221], 1, s[30:31]
	v_lshl_add_u64 v[60:61], v[218:219], 1, s[30:31]
	global_load_dwordx4 v[60:63], v[60:61], off
	s_nop 0
	global_load_dwordx4 v[64:67], v[64:65], off

; #define LAS __attribute__((address_space(3)))
; __device__ __forceinline__ unsigned pk2(float lo, float hi) { return f2bf(lo) | (f2bf(hi) << 16); }
; __device__ __forceinline__ f32x4 mfma16(bf16x8 a, bf16x8 b, f32x4 c) { return __builtin_amdgcn_mfma_f32_16x16x32_bf16(a, b, c, 0, 0, 0); }
; __device__ __forceinline__ void gla_scan_wg(const Ctx& F, int h, int sl) {
;     ...
;                 { const int nn = (n + 2 < 256) ? n + 2 : 255; ls_load(ring[(j + 2) % 3], QT, KDTb, ATTb, VTb, GLAST, h, nn, w, fr, fq, dv0, dk0); }
;                 const LS& x = ring[j % 3];
;                 if (publish && tid == 0) __hip_atomic_store(prog, n, __ATOMIC_RELAXED, __HIP_MEMORY_SCOPE_AGENT);
;                 u32x4 sp; sp.x = pk2(s0[0], s0[1]); sp.y = pk2(s0[2], s0[3]); sp.z = pk2(s1[0], s1[1]); sp.w = pk2(s1[2], s1[3]);
;                 const bf16x8 sf = __builtin_bit_cast(bf16x8, sp);
;                 f32x4 op[4];
; #pragma unroll
;                 for (int mt = 0; mt < 4; ++mt) op[mt] = mfma16(sf, x.qf[mt], (f32x4){0.f, 0.f, 0.f, 0.f});
;                 if (w < 4) {
;                     f32x4 oi = (f32x4){0.f, 0.f, 0.f, 0.f};
; #pragma unroll
;                     for (int ks = 0; ks < 2; ++ks) oi = mfma16(x.vf[ks], x.af[ks], oi);
; #pragma unroll
;                     for (int mt = 0; mt < 4; ++mt) if (mt == w) op[mt] += oi;
;                 }
; #pragma unroll
;                 for (int mt = 0; mt < 4; ++mt) *(LAS f32x4*)(OP + ((buf * 8 + w) * 64 + mt * 16 + fr) * 16 + fq * 4) = op[mt];
;                 f32x4 u0 = (f32x4){0.f, 0.f, 0.f, 0.f}, u1 = u0;
; #pragma unroll
;                 for (int ks = 0; ks < 2; ++ks) { u0 = mfma16(x.kf[0][ks], x.vf[ks], u0); u1 = mfma16(x.kf[1][ks], x.vf[ks], u1); }
;                 s0 = s0 * x.g0 + u0; s1 = s1 * x.g1 + u1;
;                 asm volatile("s_waitcnt lgkmcnt(0)" ::: "memory"); __builtin_amdgcn_s_barrier(); asm volatile("" ::: "memory");
;                 { const int e = tid * 2; float a = 0.f, b = 0.f;
; #pragma unroll
;                     for (int ww = 0; ww < 8; ++ww) { const f32x2 xx = *(const LAS f32x2*)(OP + (buf * 8 + ww) * 1024 + e); a += xx[0]; b += xx[1]; }
;                     *(unsigned*)(O + ((size_t)(h * 32 + (dv0 >> 4)) * SEQ + t0) * 16 + e) = pk2(a, b); }
.LBB0_1762:
	ds_write_b128 v215, v[164:167]
	ds_write_b128 v215, v[140:143] offset:1024
	s_nop 0
	ds_write_b128 v215, v[112:115] offset:2048
	s_nop 0
	ds_write_b128 v215, v[108:111] offset:3072
	s_waitcnt lgkmcnt(0)
	s_barrier
	ds_read2st64_b64 v[112:115], v213 offset1:8
	s_waitcnt vmcnt(29)
	v_mfma_f32_16x16x32_bf16 v[108:111], v[132:135], v[136:139], 0
	s_add_i32 s47, s46, 3
	s_min_u32 s14, s47, 0xfd
	s_add_i32 s31, s14, 2
	v_mfma_f32_16x16x32_bf16 v[186:189], v[128:131], v[136:139], 0
	ds_read2st64_b64 v[128:131], v213 offset0:16 offset1:24
	ds_read2st64_b64 v[132:135], v213 offset0:32 offset1:40
	ds_read2st64_b64 v[136:139], v213 offset0:48 offset1:56
	s_waitcnt lgkmcnt(3)
	v_pk_add_f32 v[112:113], v[112:113], 0 op_sel_hi:[1,0]
	s_add_i32 s30, s31, s35
	v_pk_add_f32 v[112:113], v[112:113], v[114:115]
	s_lshl_b32 s14, s30, 15
	s_waitcnt lgkmcnt(2)
	v_pk_add_f32 v[112:113], v[112:113], v[128:129]
	s_waitcnt vmcnt(28)
	v_mfma_f32_16x16x32_bf16 v[108:111], v[124:127], v[208:211], v[108:111]
	v_add_f32_e64 v112, v112, v130
	v_add_f32_e64 v113, v113, v131
	s_waitcnt lgkmcnt(1)
	v_pk_add_f32 v[112:113], v[112:113], v[132:133]
	s_nop 0
	v_pk_add_f32 v[112:113], v[112:113], v[134:135]
	s_waitcnt lgkmcnt(0)
	v_pk_add_f32 v[112:113], v[112:113], v[136:137]
	s_nop 0
	v_pk_add_f32 v[112:113], v[112:113], v[138:139]
	s_nop 0
	v_and_b32_sdwa v114, v112, v243 dst_sel:DWORD dst_unused:UNUSED_PAD src0_sel:WORD_1 src1_sel:DWORD
	v_and_b32_sdwa v81, v113, v243 dst_sel:DWORD dst_unused:UNUSED_PAD src0_sel:WORD_1 src1_sel:DWORD
	v_add3_u32 v112, v112, v114, s40
	v_add3_u32 v81, v113, v81, s40
	v_lshrrev_b32_e32 v112, 16, v112
	v_and_or_b32 v81, v81, s41, v112
	v_add_co_u32_e32 v112, vcc, s45, v240
	s_nop 1
	v_addc_co_u32_e32 v113, vcc, 0, v241, vcc
	global_store_dword v[112:113], v81, off nt
	v_lshl_add_u64 v[112:113], v[222:223], 0, s[14:15]
	global_load_dwordx4 v[164:167], v[112:113], off
	global_load_dwordx4 v[168:171], v[112:113], off offset:1024
	global_load_dwordx4 v[172:175], v[112:113], off offset:2048
	global_load_dwordx4 v[176:179], v[112:113], off offset:3072
	v_lshl_add_u64 v[112:113], v[224:225], 0, s[14:15]
	s_lshl_b32 s14, s30, 16
	global_load_dwordx4 v[132:135], v[112:113], off
	global_load_dwordx4 v[124:127], v[112:113], off offset:1024
	global_load_dwordx4 v[136:139], v[112:113], off offset:2048
	global_load_dwordx4 v[128:131], v[112:113], off offset:3072
	v_lshl_add_u64 v[112:113], v[226:227], 0, s[14:15]
	s_lshl_b32 s14, s31, 12
	global_load_dwordx4 v[148:151], v[112:113], off
	global_load_dwordx4 v[144:147], v[112:113], off offset:1024
	v_lshl_add_u64 v[112:113], v[216:217], 0, s[14:15]
	global_load_dwordx4 v[152:155], v[112:113], off
	global_load_dwordx4 v[140:143], v[112:113], off offset:64
	v_mfma_f32_16x16x32_bf16 v[112:115], v[204:207], v[208:211], v[186:189]
	s_and_b64 vcc, exec, s[12:13]
	s_cbranch_vccnz .LBB0_1764
	s_lshl_b32 s14, s30, 13
	s_add_u32 s30, s3, s14
	s_addc_u32 s31, s34, 0
	s_waitcnt vmcnt(39)
	v_lshl_add_u64 v[104:105], v[220:221], 1, s[30:31]
	v_lshl_add_u64 v[100:101], v[218:219], 1, s[30:31]
	global_load_dwordx4 v[100:103], v[100:101], off
	s_nop 0
	global_load_dwordx4 v[104:107], v[104:105], off

; #define LAS __attribute__((address_space(3)))
; __device__ __forceinline__ unsigned pk2(float lo, float hi) { return f2bf(lo) | (f2bf(hi) << 16); }
; __device__ __forceinline__ f32x4 mfma16(bf16x8 a, bf16x8 b, f32x4 c) { return __builtin_amdgcn_mfma_f32_16x16x32_bf16(a, b, c, 0, 0, 0); }
; __device__ __forceinline__ void gla_scan_wg(const Ctx& F, int h, int sl) {
;     ...
;                 for (int mt = 0; mt < 4; ++mt) *(LAS f32x4*)(OP + ((buf * 8 + w) * 64 + mt * 16 + fr) * 16 + fq * 4) = op[mt];
;                 f32x4 u0 = (f32x4){0.f, 0.f, 0.f, 0.f}, u1 = u0;
; #pragma unroll
;                 for (int ks = 0; ks < 2; ++ks) { u0 = mfma16(x.kf[0][ks], x.vf[ks], u0); u1 = mfma16(x.kf[1][ks], x.vf[ks], u1); }
;                 s0 = s0 * x.g0 + u0; s1 = s1 * x.g1 + u1;
;                 asm volatile("s_waitcnt lgkmcnt(0)" ::: "memory"); __builtin_amdgcn_s_barrier(); asm volatile("" ::: "memory");
;                 { const int e = tid * 2; float a = 0.f, b = 0.f;
; #pragma unroll
;                     for (int ww = 0; ww < 8; ++ww) { const f32x2 xx = *(const LAS f32x2*)(OP + (buf * 8 + ww) * 1024 + e); a += xx[0]; b += xx[1]; }
;                     *(unsigned*)(O + ((size_t)(h * 32 + (dv0 >> 4)) * SEQ + t0) * 16 + e) = pk2(a, b); }
.LBB0_1770:
	ds_write_b128 v215, v[184:187] offset:32768
	ds_write_b128 v215, v[180:183] offset:33792
	s_waitcnt vmcnt(29)
	v_mfma_f32_16x16x32_bf16 v[180:183], v[4:7], v[24:27], 0
	ds_write_b128 v215, v[112:115] offset:34816
	ds_write_b128 v215, v[108:111] offset:35840
	s_waitcnt lgkmcnt(0)
	s_barrier
	v_mfma_f32_16x16x32_bf16 v[108:111], v[8:11], v[24:27], 0
	ds_read2st64_b64 v[184:187], v213 offset0:64 offset1:72
	s_cmpk_gt_u32 s46, 0xfb
	s_waitcnt vmcnt(28)
	v_mfma_f32_16x16x32_bf16 v[112:115], v[0:3], v[28:31], v[180:183]
	s_nop 2
	ds_read2st64_b64 v[180:183], v213 offset0:80 offset1:88
	ds_read2st64_b64 v[194:197], v213 offset0:96 offset1:104
	ds_read2st64_b64 v[198:201], v213 offset0:112 offset1:120
	v_mfma_f32_16x16x32_bf16 v[202:205], v[16:19], v[28:31], v[108:111]
	s_waitcnt vmcnt(27)
	s_nop 1
	v_pk_fma_f32 v[110:111], v[158:159], v[190:191], v[114:115]
	v_pk_fma_f32 v[108:109], v[156:157], v[192:193], v[112:113]
	s_waitcnt vmcnt(26)
	s_nop 1
	v_pk_fma_f32 v[114:115], v[162:163], v[82:83], v[204:205]
	s_waitcnt lgkmcnt(3)
	v_pk_add_f32 v[82:83], v[184:185], 0 op_sel_hi:[1,0]
	v_pk_fma_f32 v[112:113], v[160:161], v[188:189], v[202:203]
	v_pk_add_f32 v[82:83], v[82:83], v[186:187]
	s_waitcnt lgkmcnt(2)
	v_pk_add_f32 v[82:83], v[82:83], v[180:181]
	s_nop 0
	v_pk_add_f32 v[82:83], v[82:83], v[182:183]
	s_waitcnt lgkmcnt(1)
	v_pk_add_f32 v[82:83], v[82:83], v[194:195]
	s_nop 0
	v_pk_add_f32 v[82:83], v[82:83], v[196:197]
	s_waitcnt lgkmcnt(0)
	v_pk_add_f32 v[82:83], v[82:83], v[198:199]
	s_nop 0
	v_pk_add_f32 v[82:83], v[82:83], v[200:201]
	s_nop 0
	v_and_b32_sdwa v180, v82, v243 dst_sel:DWORD dst_unused:UNUSED_PAD src0_sel:WORD_1 src1_sel:DWORD
	v_and_b32_sdwa v81, v83, v243 dst_sel:DWORD dst_unused:UNUSED_PAD src0_sel:WORD_1 src1_sel:DWORD
	v_add3_u32 v82, v82, v180, s40
	v_add3_u32 v81, v83, v81, s40
	v_lshrrev_b32_e32 v82, 16, v82
	v_and_or_b32 v81, v81, s41, v82
	v_add_co_u32_e32 v82, vcc, 0xac01000, v240
	s_nop 1
	v_addc_co_u32_e32 v83, vcc, 0, v241, vcc
	global_store_dword v[82:83], v81, off offset:2048 nt
	s_cbranch_scc0 .LBB0_1783
	s_cmpk_gt_u32 s46, 0xfa
	s_cbranch_scc0 .LBB0_1792

; #define LAS __attribute__((address_space(3)))
; __device__ __forceinline__ unsigned pk2(float lo, float hi) { return f2bf(lo) | (f2bf(hi) << 16); }
; __device__ __forceinline__ f32x4 mfma16(bf16x8 a, bf16x8 b, f32x4 c) { return __builtin_amdgcn_mfma_f32_16x16x32_bf16(a, b, c, 0, 0, 0); }
; __device__ __forceinline__ void gla_scan_wg(const Ctx& F, int h, int sl) {
;     ...
;                 for (int mt = 0; mt < 4; ++mt) *(LAS f32x4*)(OP + ((buf * 8 + w) * 64 + mt * 16 + fr) * 16 + fq * 4) = op[mt];
;                 f32x4 u0 = (f32x4){0.f, 0.f, 0.f, 0.f}, u1 = u0;
; #pragma unroll
;                 for (int ks = 0; ks < 2; ++ks) { u0 = mfma16(x.kf[0][ks], x.vf[ks], u0); u1 = mfma16(x.kf[1][ks], x.vf[ks], u1); }
;                 s0 = s0 * x.g0 + u0; s1 = s1 * x.g1 + u1;
;                 asm volatile("s_waitcnt lgkmcnt(0)" ::: "memory"); __builtin_amdgcn_s_barrier(); asm volatile("" ::: "memory");
;                 { const int e = tid * 2; float a = 0.f, b = 0.f;
; #pragma unroll
;                     for (int ww = 0; ww < 8; ++ww) { const f32x2 xx = *(const LAS f32x2*)(OP + (buf * 8 + ww) * 1024 + e); a += xx[0]; b += xx[1]; }
;                     *(unsigned*)(O + ((size_t)(h * 32 + (dv0 >> 4)) * SEQ + t0) * 16 + e) = pk2(a, b); }
.LBB0_1791:
	ds_write_b128 v215, v[192:195]
	ds_write_b128 v215, v[188:191] offset:1024
	s_nop 0
	ds_write_b128 v215, v[184:187] offset:2048
	s_nop 0
	ds_write_b128 v215, v[180:183] offset:3072
	s_waitcnt lgkmcnt(0)
	s_barrier
	ds_read2st64_b64 v[184:187], v213 offset1:8
	ds_read2st64_b64 v[192:195], v213 offset0:16 offset1:24
	ds_read2st64_b64 v[196:199], v213 offset0:32 offset1:40
	ds_read2st64_b64 v[200:203], v213 offset0:48 offset1:56
	s_waitcnt vmcnt(29)
	v_mfma_f32_16x16x32_bf16 v[180:183], v[56:59], v[72:75], 0
	s_waitcnt lgkmcnt(3)
	v_pk_add_f32 v[82:83], v[184:185], 0 op_sel_hi:[1,0]
	s_nop 0
	v_pk_add_f32 v[82:83], v[82:83], v[186:187]
	v_mfma_f32_16x16x32_bf16 v[188:191], v[44:47], v[72:75], 0
	s_waitcnt lgkmcnt(2)
	v_pk_add_f32 v[82:83], v[82:83], v[192:193]
	s_nop 0
	v_pk_add_f32 v[82:83], v[82:83], v[194:195]
	s_waitcnt vmcnt(28)
	v_mfma_f32_16x16x32_bf16 v[180:183], v[52:55], v[68:71], v[180:183]
	s_waitcnt lgkmcnt(1)
	v_pk_add_f32 v[82:83], v[82:83], v[196:197]
	s_nop 0
	v_pk_add_f32 v[82:83], v[82:83], v[198:199]
	v_mfma_f32_16x16x32_bf16 v[188:191], v[40:43], v[68:71], v[188:191]
	s_waitcnt lgkmcnt(0)
	v_pk_add_f32 v[82:83], v[82:83], v[200:201]
	s_waitcnt vmcnt(26)
	v_pk_fma_f32 v[112:113], v[120:121], v[112:113], v[180:181]
	v_pk_add_f32 v[82:83], v[82:83], v[202:203]
	v_pk_fma_f32 v[114:115], v[122:123], v[114:115], v[182:183]
	v_and_b32_sdwa v180, v82, v243 dst_sel:DWORD dst_unused:UNUSED_PAD src0_sel:WORD_1 src1_sel:DWORD
	v_and_b32_sdwa v81, v83, v243 dst_sel:DWORD dst_unused:UNUSED_PAD src0_sel:WORD_1 src1_sel:DWORD
	v_add3_u32 v82, v82, v180, s40
	v_add3_u32 v81, v83, v81, s40
	v_lshrrev_b32_e32 v82, 16, v82
	v_and_or_b32 v81, v81, s41, v82
	v_add_co_u32_e32 v82, vcc, 0xac02000, v240
	v_pk_fma_f32 v[110:111], v[118:119], v[110:111], v[190:191]
	v_pk_fma_f32 v[108:109], v[116:117], v[108:109], v[188:189]
	v_addc_co_u32_e32 v83, vcc, 0, v241, vcc
	global_store_dword v[82:83], v81, off nt
	s_cmpk_gt_u32 s46, 0xfa
	s_cbranch_scc1 .LBB0_1772

; #define LAS __attribute__((address_space(3)))
; __device__ __forceinline__ unsigned pk2(float lo, float hi) { return f2bf(lo) | (f2bf(hi) << 16); }
; __device__ __forceinline__ f32x4 mfma16(bf16x8 a, bf16x8 b, f32x4 c) { return __builtin_amdgcn_mfma_f32_16x16x32_bf16(a, b, c, 0, 0, 0); }
; __device__ __forceinline__ void gla_scan_wg(const Ctx& F, int h, int sl) {
;     ...
;                 for (int mt = 0; mt < 4; ++mt) *(LAS f32x4*)(OP + ((buf * 8 + w) * 64 + mt * 16 + fr) * 16 + fq * 4) = op[mt];
;                 f32x4 u0 = (f32x4){0.f, 0.f, 0.f, 0.f}, u1 = u0;
; #pragma unroll
;                 for (int ks = 0; ks < 2; ++ks) { u0 = mfma16(x.kf[0][ks], x.vf[ks], u0); u1 = mfma16(x.kf[1][ks], x.vf[ks], u1); }
;                 s0 = s0 * x.g0 + u0; s1 = s1 * x.g1 + u1;
;                 asm volatile("s_waitcnt lgkmcnt(0)" ::: "memory"); __builtin_amdgcn_s_barrier(); asm volatile("" ::: "memory");
;                 { const int e = tid * 2; float a = 0.f, b = 0.f;
; #pragma unroll
;                     for (int ww = 0; ww < 8; ++ww) { const f32x2 xx = *(const LAS f32x2*)(OP + (buf * 8 + ww) * 1024 + e); a += xx[0]; b += xx[1]; }
;                     *(unsigned*)(O + ((size_t)(h * 32 + (dv0 >> 4)) * SEQ + t0) * 16 + e) = pk2(a, b); }
.LBB0_1800:
	ds_write_b128 v215, v[192:195] offset:32768
	ds_write_b128 v215, v[188:191] offset:33792
	s_nop 0
	ds_write_b128 v215, v[184:187] offset:34816
	s_nop 0
	ds_write_b128 v215, v[180:183] offset:35840
	s_waitcnt lgkmcnt(0)
	s_barrier
	ds_read2st64_b64 v[184:187], v213 offset0:64 offset1:72
	ds_read2st64_b64 v[192:195], v213 offset0:80 offset1:88
	ds_read2st64_b64 v[196:199], v213 offset0:96 offset1:104
	ds_read2st64_b64 v[200:203], v213 offset0:112 offset1:120
	s_waitcnt vmcnt(16)
	v_mfma_f32_16x16x32_bf16 v[180:183], v[136:139], v[148:151], 0
	s_waitcnt lgkmcnt(3)
	v_pk_add_f32 v[82:83], v[184:185], 0 op_sel_hi:[1,0]
	s_nop 0
	v_pk_add_f32 v[82:83], v[82:83], v[186:187]
	v_mfma_f32_16x16x32_bf16 v[188:191], v[132:135], v[148:151], 0
	s_waitcnt lgkmcnt(2)
	v_pk_add_f32 v[82:83], v[82:83], v[192:193]
	s_nop 0
	v_pk_add_f32 v[82:83], v[82:83], v[194:195]
	s_waitcnt vmcnt(15)
	v_mfma_f32_16x16x32_bf16 v[180:183], v[128:131], v[144:147], v[180:183]
	s_waitcnt lgkmcnt(1)
	v_pk_add_f32 v[82:83], v[82:83], v[196:197]
	s_nop 0
	v_pk_add_f32 v[82:83], v[82:83], v[198:199]
	v_mfma_f32_16x16x32_bf16 v[188:191], v[124:127], v[144:147], v[188:191]
	s_waitcnt lgkmcnt(0)
	v_pk_add_f32 v[82:83], v[82:83], v[200:201]
	s_waitcnt vmcnt(13)
	v_pk_fma_f32 v[112:113], v[140:141], v[112:113], v[180:181]
	v_pk_add_f32 v[82:83], v[82:83], v[202:203]
	v_pk_fma_f32 v[114:115], v[142:143], v[114:115], v[182:183]
	v_and_b32_sdwa v180, v82, v243 dst_sel:DWORD dst_unused:UNUSED_PAD src0_sel:WORD_1 src1_sel:DWORD
	v_and_b32_sdwa v81, v83, v243 dst_sel:DWORD dst_unused:UNUSED_PAD src0_sel:WORD_1 src1_sel:DWORD
	v_add3_u32 v82, v82, v180, s40
	v_add3_u32 v81, v83, v81, s40
	v_lshrrev_b32_e32 v82, 16, v82
	v_and_or_b32 v81, v81, s41, v82
	v_add_co_u32_e32 v82, vcc, 0xac02000, v240
	v_pk_fma_f32 v[110:111], v[154:155], v[110:111], v[190:191]
	v_pk_fma_f32 v[108:109], v[152:153], v[108:109], v[188:189]
	v_addc_co_u32_e32 v83, vcc, 0, v241, vcc
	global_store_dword v[82:83], v81, off offset:2048 nt
	s_cmpk_gt_u32 s46, 0xf9
	s_cbranch_scc1 .LBB0_1773

; #define LAS __attribute__((address_space(3)))
; __device__ __forceinline__ unsigned pk2(float lo, float hi) { return f2bf(lo) | (f2bf(hi) << 16); }
; __device__ __forceinline__ f32x4 mfma16(bf16x8 a, bf16x8 b, f32x4 c) { return __builtin_amdgcn_mfma_f32_16x16x32_bf16(a, b, c, 0, 0, 0); }
; __device__ __forceinline__ void gla_scan_wg(const Ctx& F, int h, int sl) {
;     ...
;                 for (int mt = 0; mt < 4; ++mt) *(LAS f32x4*)(OP + ((buf * 8 + w) * 64 + mt * 16 + fr) * 16 + fq * 4) = op[mt];
;                 f32x4 u0 = (f32x4){0.f, 0.f, 0.f, 0.f}, u1 = u0;
; #pragma unroll
;                 for (int ks = 0; ks < 2; ++ks) { u0 = mfma16(x.kf[0][ks], x.vf[ks], u0); u1 = mfma16(x.kf[1][ks], x.vf[ks], u1); }
;                 s0 = s0 * x.g0 + u0; s1 = s1 * x.g1 + u1;
;                 asm volatile("s_waitcnt lgkmcnt(0)" ::: "memory"); __builtin_amdgcn_s_barrier(); asm volatile("" ::: "memory");
;                 { const int e = tid * 2; float a = 0.f, b = 0.f;
; #pragma unroll
;                     for (int ww = 0; ww < 8; ++ww) { const f32x2 xx = *(const LAS f32x2*)(OP + (buf * 8 + ww) * 1024 + e); a += xx[0]; b += xx[1]; }
;                     *(unsigned*)(O + ((size_t)(h * 32 + (dv0 >> 4)) * SEQ + t0) * 16 + e) = pk2(a, b); }
.LBB0_1809:
	s_nop 1
	ds_write_b128 v215, v[192:195]
	ds_write_b128 v215, v[188:191] offset:1024
	ds_write_b128 v215, v[156:159] offset:2048
	ds_write_b128 v215, v[160:163] offset:3072
	s_waitcnt lgkmcnt(0)
	s_barrier
	ds_read2st64_b64 v[160:163], v213 offset1:8
	ds_read2st64_b64 v[192:195], v213 offset0:16 offset1:24
	ds_read2st64_b64 v[196:199], v213 offset0:32 offset1:40
	ds_read2st64_b64 v[200:203], v213 offset0:48 offset1:56
	v_mfma_f32_16x16x32_bf16 v[156:159], v[56:59], v[72:75], 0
	s_waitcnt lgkmcnt(3)
	v_pk_add_f32 v[82:83], v[160:161], 0 op_sel_hi:[1,0]
	s_nop 0
	v_pk_add_f32 v[82:83], v[82:83], v[162:163]
	v_mfma_f32_16x16x32_bf16 v[188:191], v[44:47], v[72:75], 0
	s_waitcnt lgkmcnt(2)
	v_pk_add_f32 v[82:83], v[82:83], v[192:193]
	s_nop 0
	v_pk_add_f32 v[82:83], v[82:83], v[194:195]
	v_mfma_f32_16x16x32_bf16 v[156:159], v[52:55], v[68:71], v[156:159]
	s_waitcnt lgkmcnt(1)
	v_pk_add_f32 v[82:83], v[82:83], v[196:197]
	s_nop 0
	v_pk_add_f32 v[82:83], v[82:83], v[198:199]
	v_mfma_f32_16x16x32_bf16 v[188:191], v[40:43], v[68:71], v[188:191]
	s_waitcnt lgkmcnt(0)
	v_pk_add_f32 v[82:83], v[82:83], v[200:201]
	s_nop 0
	v_pk_fma_f32 v[112:113], v[120:121], v[112:113], v[156:157]
	v_pk_add_f32 v[82:83], v[82:83], v[202:203]
	v_pk_fma_f32 v[114:115], v[122:123], v[114:115], v[158:159]
	v_and_b32_sdwa v156, v82, v243 dst_sel:DWORD dst_unused:UNUSED_PAD src0_sel:WORD_1 src1_sel:DWORD
	v_and_b32_sdwa v81, v83, v243 dst_sel:DWORD dst_unused:UNUSED_PAD src0_sel:WORD_1 src1_sel:DWORD
	v_add3_u32 v82, v82, v156, s40
	v_add3_u32 v81, v83, v81, s40
	v_lshrrev_b32_e32 v82, 16, v82
	v_and_or_b32 v81, v81, s41, v82
	v_add_co_u32_e32 v82, vcc, 0xac05000, v240
	v_pk_fma_f32 v[110:111], v[118:119], v[110:111], v[190:191]
	v_pk_fma_f32 v[108:109], v[116:117], v[108:109], v[188:189]
	v_addc_co_u32_e32 v83, vcc, 0, v241, vcc
	global_store_dword v[82:83], v81, off nt
	s_cmpk_gt_u32 s46, 0xf4
	s_cbranch_scc1 .LBB0_1736
	s_branch .LBB0_1841

; #define LAS __attribute__((address_space(3)))
; __device__ __forceinline__ unsigned pk2(float lo, float hi) { return f2bf(lo) | (f2bf(hi) << 16); }
; __device__ __forceinline__ f32x4 mfma16(bf16x8 a, bf16x8 b, f32x4 c) { return __builtin_amdgcn_mfma_f32_16x16x32_bf16(a, b, c, 0, 0, 0); }
; __device__ __forceinline__ void gla_scan_wg(const Ctx& F, int h, int sl) {
;     ...
;                 for (int mt = 0; mt < 4; ++mt) *(LAS f32x4*)(OP + ((buf * 8 + w) * 64 + mt * 16 + fr) * 16 + fq * 4) = op[mt];
;                 f32x4 u0 = (f32x4){0.f, 0.f, 0.f, 0.f}, u1 = u0;
; #pragma unroll
;                 for (int ks = 0; ks < 2; ++ks) { u0 = mfma16(x.kf[0][ks], x.vf[ks], u0); u1 = mfma16(x.kf[1][ks], x.vf[ks], u1); }
;                 s0 = s0 * x.g0 + u0; s1 = s1 * x.g1 + u1;
;                 asm volatile("s_waitcnt lgkmcnt(0)" ::: "memory"); __builtin_amdgcn_s_barrier(); asm volatile("" ::: "memory");
;                 { const int e = tid * 2; float a = 0.f, b = 0.f;
; #pragma unroll
;                     for (int ww = 0; ww < 8; ++ww) { const f32x2 xx = *(const LAS f32x2*)(OP + (buf * 8 + ww) * 1024 + e); a += xx[0]; b += xx[1]; }
;                     *(unsigned*)(O + ((size_t)(h * 32 + (dv0 >> 4)) * SEQ + t0) * 16 + e) = pk2(a, b); }
.LBB0_1812:
	ds_write_b128 v215, v[192:195]
	ds_write_b128 v215, v[188:191] offset:1024
	s_nop 0
	ds_write_b128 v215, v[180:183] offset:2048
	s_nop 0
	ds_write_b128 v215, v[184:187] offset:3072
	s_waitcnt lgkmcnt(0)
	s_barrier
	ds_read2st64_b64 v[184:187], v213 offset1:8
	ds_read2st64_b64 v[192:195], v213 offset0:16 offset1:24
	ds_read2st64_b64 v[196:199], v213 offset0:32 offset1:40
	ds_read2st64_b64 v[200:203], v213 offset0:48 offset1:56
	s_waitcnt vmcnt(16)
	v_mfma_f32_16x16x32_bf16 v[180:183], v[8:11], v[24:27], 0
	s_waitcnt lgkmcnt(3)
	v_pk_add_f32 v[82:83], v[184:185], 0 op_sel_hi:[1,0]
	s_nop 0
	v_pk_add_f32 v[82:83], v[82:83], v[186:187]
	v_mfma_f32_16x16x32_bf16 v[188:191], v[4:7], v[24:27], 0
	s_waitcnt lgkmcnt(2)
	v_pk_add_f32 v[82:83], v[82:83], v[192:193]
	s_nop 0
	v_pk_add_f32 v[82:83], v[82:83], v[194:195]
	s_waitcnt vmcnt(15)
	v_mfma_f32_16x16x32_bf16 v[180:183], v[16:19], v[28:31], v[180:183]
	s_waitcnt lgkmcnt(1)
	v_pk_add_f32 v[82:83], v[82:83], v[196:197]
	s_nop 0
	v_pk_add_f32 v[82:83], v[82:83], v[198:199]
	v_mfma_f32_16x16x32_bf16 v[188:191], v[0:3], v[28:31], v[188:191]
	s_waitcnt lgkmcnt(0)
	v_pk_add_f32 v[82:83], v[82:83], v[200:201]
	s_waitcnt vmcnt(13)
	v_pk_fma_f32 v[112:113], v[160:161], v[112:113], v[180:181]
	v_pk_add_f32 v[82:83], v[82:83], v[202:203]
	v_pk_fma_f32 v[114:115], v[162:163], v[114:115], v[182:183]
	v_and_b32_sdwa v180, v82, v243 dst_sel:DWORD dst_unused:UNUSED_PAD src0_sel:WORD_1 src1_sel:DWORD
	v_and_b32_sdwa v81, v83, v243 dst_sel:DWORD dst_unused:UNUSED_PAD src0_sel:WORD_1 src1_sel:DWORD
	v_add3_u32 v82, v82, v180, s40
	v_add3_u32 v81, v83, v81, s40
	v_lshrrev_b32_e32 v82, 16, v82
	v_and_or_b32 v81, v81, s41, v82
	v_add_co_u32_e32 v82, vcc, 0xac03000, v240
	v_pk_fma_f32 v[110:111], v[158:159], v[110:111], v[190:191]
	v_pk_fma_f32 v[108:109], v[156:157], v[108:109], v[188:189]
	v_addc_co_u32_e32 v83, vcc, 0, v241, vcc
	global_store_dword v[82:83], v81, off nt
	s_cmpk_gt_u32 s46, 0xf8
	s_cbranch_scc1 .LBB0_1774

; #define LAS __attribute__((address_space(3)))
; __device__ __forceinline__ unsigned pk2(float lo, float hi) { return f2bf(lo) | (f2bf(hi) << 16); }
; __device__ __forceinline__ f32x4 mfma16(bf16x8 a, bf16x8 b, f32x4 c) { return __builtin_amdgcn_mfma_f32_16x16x32_bf16(a, b, c, 0, 0, 0); }
; __device__ __forceinline__ void gla_scan_wg(const Ctx& F, int h, int sl) {
;     ...
;                 for (int mt = 0; mt < 4; ++mt) *(LAS f32x4*)(OP + ((buf * 8 + w) * 64 + mt * 16 + fr) * 16 + fq * 4) = op[mt];
;                 f32x4 u0 = (f32x4){0.f, 0.f, 0.f, 0.f}, u1 = u0;
; #pragma unroll
;                 for (int ks = 0; ks < 2; ++ks) { u0 = mfma16(x.kf[0][ks], x.vf[ks], u0); u1 = mfma16(x.kf[1][ks], x.vf[ks], u1); }
;                 s0 = s0 * x.g0 + u0; s1 = s1 * x.g1 + u1;
;                 asm volatile("s_waitcnt lgkmcnt(0)" ::: "memory"); __builtin_amdgcn_s_barrier(); asm volatile("" ::: "memory");
;                 { const int e = tid * 2; float a = 0.f, b = 0.f;
; #pragma unroll
;                     for (int ww = 0; ww < 8; ++ww) { const f32x2 xx = *(const LAS f32x2*)(OP + (buf * 8 + ww) * 1024 + e); a += xx[0]; b += xx[1]; }
;                     *(unsigned*)(O + ((size_t)(h * 32 + (dv0 >> 4)) * SEQ + t0) * 16 + e) = pk2(a, b); }
.LBB0_1821:
	s_nop 1
	ds_write_b128 v215, v[192:195] offset:32768
	ds_write_b128 v215, v[188:191] offset:33792
	ds_write_b128 v215, v[180:183] offset:34816
	ds_write_b128 v215, v[184:187] offset:35840
	s_waitcnt lgkmcnt(0)
	s_barrier
	ds_read2st64_b64 v[184:187], v213 offset0:64 offset1:72
	ds_read2st64_b64 v[192:195], v213 offset0:80 offset1:88
	ds_read2st64_b64 v[196:199], v213 offset0:96 offset1:104
	ds_read2st64_b64 v[200:203], v213 offset0:112 offset1:120
	v_mfma_f32_16x16x32_bf16 v[180:183], v[56:59], v[72:75], 0
	s_waitcnt lgkmcnt(3)
	v_pk_add_f32 v[82:83], v[184:185], 0 op_sel_hi:[1,0]
	s_nop 0
	v_pk_add_f32 v[82:83], v[82:83], v[186:187]
	v_mfma_f32_16x16x32_bf16 v[188:191], v[44:47], v[72:75], 0
	s_waitcnt lgkmcnt(2)
	v_pk_add_f32 v[82:83], v[82:83], v[192:193]
	s_nop 0
	v_pk_add_f32 v[82:83], v[82:83], v[194:195]
	v_mfma_f32_16x16x32_bf16 v[180:183], v[52:55], v[68:71], v[180:183]
	s_waitcnt lgkmcnt(1)
	v_pk_add_f32 v[82:83], v[82:83], v[196:197]
	s_nop 0
	v_pk_add_f32 v[82:83], v[82:83], v[198:199]
	v_mfma_f32_16x16x32_bf16 v[188:191], v[40:43], v[68:71], v[188:191]
	s_waitcnt lgkmcnt(0)
	v_pk_add_f32 v[82:83], v[82:83], v[200:201]
	s_waitcnt vmcnt(13)
	v_pk_fma_f32 v[112:113], v[120:121], v[112:113], v[180:181]
	v_pk_add_f32 v[82:83], v[82:83], v[202:203]
	v_pk_fma_f32 v[114:115], v[122:123], v[114:115], v[182:183]
	v_and_b32_sdwa v180, v82, v243 dst_sel:DWORD dst_unused:UNUSED_PAD src0_sel:WORD_1 src1_sel:DWORD
	v_and_b32_sdwa v81, v83, v243 dst_sel:DWORD dst_unused:UNUSED_PAD src0_sel:WORD_1 src1_sel:DWORD
	v_add3_u32 v82, v82, v180, s40
	v_add3_u32 v81, v83, v81, s40
	v_lshrrev_b32_e32 v82, 16, v82
	v_and_or_b32 v81, v81, s41, v82
	v_add_co_u32_e32 v82, vcc, 0xac03000, v240
	v_pk_fma_f32 v[110:111], v[118:119], v[110:111], v[190:191]
	v_pk_fma_f32 v[108:109], v[116:117], v[108:109], v[188:189]
	v_addc_co_u32_e32 v83, vcc, 0, v241, vcc
	global_store_dword v[82:83], v81, off offset:2048 nt
	s_cmpk_gt_u32 s46, 0xf7
	s_cbranch_scc1 .LBB0_1775

; #define LAS __attribute__((address_space(3)))
; __device__ __forceinline__ unsigned pk2(float lo, float hi) { return f2bf(lo) | (f2bf(hi) << 16); }
; __device__ __forceinline__ f32x4 mfma16(bf16x8 a, bf16x8 b, f32x4 c) { return __builtin_amdgcn_mfma_f32_16x16x32_bf16(a, b, c, 0, 0, 0); }
; __device__ __forceinline__ void gla_scan_wg(const Ctx& F, int h, int sl) {
;     ...
;                 for (int mt = 0; mt < 4; ++mt) *(LAS f32x4*)(OP + ((buf * 8 + w) * 64 + mt * 16 + fr) * 16 + fq * 4) = op[mt];
;                 f32x4 u0 = (f32x4){0.f, 0.f, 0.f, 0.f}, u1 = u0;
; #pragma unroll
;                 for (int ks = 0; ks < 2; ++ks) { u0 = mfma16(x.kf[0][ks], x.vf[ks], u0); u1 = mfma16(x.kf[1][ks], x.vf[ks], u1); }
;                 s0 = s0 * x.g0 + u0; s1 = s1 * x.g1 + u1;
;                 asm volatile("s_waitcnt lgkmcnt(0)" ::: "memory"); __builtin_amdgcn_s_barrier(); asm volatile("" ::: "memory");
;                 { const int e = tid * 2; float a = 0.f, b = 0.f;
; #pragma unroll
;                     for (int ww = 0; ww < 8; ++ww) { const f32x2 xx = *(const LAS f32x2*)(OP + (buf * 8 + ww) * 1024 + e); a += xx[0]; b += xx[1]; }
;                     *(unsigned*)(O + ((size_t)(h * 32 + (dv0 >> 4)) * SEQ + t0) * 16 + e) = pk2(a, b); }
.LBB0_1830:
	s_nop 1
	ds_write_b128 v215, v[192:195]
	ds_write_b128 v215, v[188:191] offset:1024
	ds_write_b128 v215, v[180:183] offset:2048
	ds_write_b128 v215, v[184:187] offset:3072
	s_waitcnt lgkmcnt(0)
	s_barrier
	ds_read2st64_b64 v[184:187], v213 offset1:8
	ds_read2st64_b64 v[192:195], v213 offset0:16 offset1:24
	ds_read2st64_b64 v[196:199], v213 offset0:32 offset1:40
	ds_read2st64_b64 v[200:203], v213 offset0:48 offset1:56
	v_mfma_f32_16x16x32_bf16 v[180:183], v[136:139], v[148:151], 0
	s_waitcnt lgkmcnt(3)
	v_pk_add_f32 v[82:83], v[184:185], 0 op_sel_hi:[1,0]
	s_nop 0
	v_pk_add_f32 v[82:83], v[82:83], v[186:187]
	v_mfma_f32_16x16x32_bf16 v[188:191], v[132:135], v[148:151], 0
	s_waitcnt lgkmcnt(2)
	v_pk_add_f32 v[82:83], v[82:83], v[192:193]
	s_nop 0
	v_pk_add_f32 v[82:83], v[82:83], v[194:195]
	v_mfma_f32_16x16x32_bf16 v[180:183], v[128:131], v[144:147], v[180:183]
	s_waitcnt lgkmcnt(1)
	v_pk_add_f32 v[82:83], v[82:83], v[196:197]
	s_nop 0
	v_pk_add_f32 v[82:83], v[82:83], v[198:199]
	v_mfma_f32_16x16x32_bf16 v[188:191], v[124:127], v[144:147], v[188:191]
	s_waitcnt lgkmcnt(0)
	v_pk_add_f32 v[82:83], v[82:83], v[200:201]
	s_waitcnt vmcnt(13)
	v_pk_fma_f32 v[112:113], v[140:141], v[112:113], v[180:181]
	v_pk_add_f32 v[82:83], v[82:83], v[202:203]
	v_pk_fma_f32 v[114:115], v[142:143], v[114:115], v[182:183]
	v_and_b32_sdwa v180, v82, v243 dst_sel:DWORD dst_unused:UNUSED_PAD src0_sel:WORD_1 src1_sel:DWORD
	v_and_b32_sdwa v81, v83, v243 dst_sel:DWORD dst_unused:UNUSED_PAD src0_sel:WORD_1 src1_sel:DWORD
	v_add3_u32 v82, v82, v180, s40
	v_add3_u32 v81, v83, v81, s40
	v_lshrrev_b32_e32 v82, 16, v82
	v_and_or_b32 v81, v81, s41, v82
	v_add_co_u32_e32 v82, vcc, 0xac04000, v240
	v_pk_fma_f32 v[110:111], v[154:155], v[110:111], v[190:191]
	v_pk_fma_f32 v[108:109], v[152:153], v[108:109], v[188:189]
	v_addc_co_u32_e32 v83, vcc, 0, v241, vcc
	global_store_dword v[82:83], v81, off nt
	s_cmpk_gt_u32 s46, 0xf6
	s_cbranch_scc1 .LBB0_1776

; #define LAS __attribute__((address_space(3)))
; __device__ __forceinline__ unsigned pk2(float lo, float hi) { return f2bf(lo) | (f2bf(hi) << 16); }
; __device__ __forceinline__ f32x4 mfma16(bf16x8 a, bf16x8 b, f32x4 c) { return __builtin_amdgcn_mfma_f32_16x16x32_bf16(a, b, c, 0, 0, 0); }
; __device__ __forceinline__ void gla_scan_wg(const Ctx& F, int h, int sl) {
;     ...
;                 for (int mt = 0; mt < 4; ++mt) *(LAS f32x4*)(OP + ((buf * 8 + w) * 64 + mt * 16 + fr) * 16 + fq * 4) = op[mt];
;                 f32x4 u0 = (f32x4){0.f, 0.f, 0.f, 0.f}, u1 = u0;
; #pragma unroll
;                 for (int ks = 0; ks < 2; ++ks) { u0 = mfma16(x.kf[0][ks], x.vf[ks], u0); u1 = mfma16(x.kf[1][ks], x.vf[ks], u1); }
;                 s0 = s0 * x.g0 + u0; s1 = s1 * x.g1 + u1;
;                 asm volatile("s_waitcnt lgkmcnt(0)" ::: "memory"); __builtin_amdgcn_s_barrier(); asm volatile("" ::: "memory");
;                 { const int e = tid * 2; float a = 0.f, b = 0.f;
; #pragma unroll
;                     for (int ww = 0; ww < 8; ++ww) { const f32x2 xx = *(const LAS f32x2*)(OP + (buf * 8 + ww) * 1024 + e); a += xx[0]; b += xx[1]; }
;                     *(unsigned*)(O + ((size_t)(h * 32 + (dv0 >> 4)) * SEQ + t0) * 16 + e) = pk2(a, b); }
.LBB0_1839:
	ds_write_b128 v215, v[192:195] offset:32768
	ds_write_b128 v215, v[188:191] offset:33792
	s_nop 0
	ds_write_b128 v215, v[180:183] offset:34816
	s_nop 0
	ds_write_b128 v215, v[184:187] offset:35840
	s_waitcnt lgkmcnt(0)
	s_barrier
	ds_read2st64_b64 v[184:187], v213 offset0:64 offset1:72
	ds_read2st64_b64 v[192:195], v213 offset0:80 offset1:88
	ds_read2st64_b64 v[196:199], v213 offset0:96 offset1:104
	ds_read2st64_b64 v[200:203], v213 offset0:112 offset1:120
	s_waitcnt vmcnt(16)
	v_mfma_f32_16x16x32_bf16 v[180:183], v[8:11], v[24:27], 0
	s_waitcnt lgkmcnt(3)
	v_pk_add_f32 v[82:83], v[184:185], 0 op_sel_hi:[1,0]
	s_nop 0
	v_pk_add_f32 v[82:83], v[82:83], v[186:187]
	v_mfma_f32_16x16x32_bf16 v[188:191], v[4:7], v[24:27], 0
	s_waitcnt lgkmcnt(2)
	v_pk_add_f32 v[82:83], v[82:83], v[192:193]
	s_nop 0
	v_pk_add_f32 v[82:83], v[82:83], v[194:195]
	s_waitcnt vmcnt(15)
	v_mfma_f32_16x16x32_bf16 v[180:183], v[16:19], v[28:31], v[180:183]
	s_waitcnt lgkmcnt(1)
	v_pk_add_f32 v[82:83], v[82:83], v[196:197]
	s_nop 0
	v_pk_add_f32 v[82:83], v[82:83], v[198:199]
	v_mfma_f32_16x16x32_bf16 v[188:191], v[0:3], v[28:31], v[188:191]
	s_waitcnt lgkmcnt(0)
	v_pk_add_f32 v[82:83], v[82:83], v[200:201]
	s_waitcnt vmcnt(13)
	v_pk_fma_f32 v[112:113], v[160:161], v[112:113], v[180:181]
	v_pk_add_f32 v[82:83], v[82:83], v[202:203]
	v_pk_fma_f32 v[114:115], v[162:163], v[114:115], v[182:183]
	v_and_b32_sdwa v180, v82, v243 dst_sel:DWORD dst_unused:UNUSED_PAD src0_sel:WORD_1 src1_sel:DWORD
	v_and_b32_sdwa v81, v83, v243 dst_sel:DWORD dst_unused:UNUSED_PAD src0_sel:WORD_1 src1_sel:DWORD
	v_add3_u32 v82, v82, v180, s40
	v_add3_u32 v81, v83, v81, s40
	v_lshrrev_b32_e32 v82, 16, v82
	v_and_or_b32 v81, v81, s41, v82
	v_add_co_u32_e32 v82, vcc, 0xac04000, v240
	v_pk_fma_f32 v[110:111], v[158:159], v[110:111], v[190:191]
	v_pk_fma_f32 v[108:109], v[156:157], v[108:109], v[188:189]
	v_addc_co_u32_e32 v83, vcc, 0, v241, vcc
	global_store_dword v[82:83], v81, off offset:2048 nt
	s_cmpk_gt_u32 s46, 0xf5
	s_cbranch_scc0 .LBB0_1777

; #define LAS __attribute__((address_space(3)))
; __device__ __forceinline__ unsigned pk2(float lo, float hi) { return f2bf(lo) | (f2bf(hi) << 16); }
; __device__ __forceinline__ f32x4 mfma16(bf16x8 a, bf16x8 b, f32x4 c) { return __builtin_amdgcn_mfma_f32_16x16x32_bf16(a, b, c, 0, 0, 0); }
; __device__ __forceinline__ void gla_scan_wg(const Ctx& F, int h, int sl) {
;     ...
;                 for (int mt = 0; mt < 4; ++mt) *(LAS f32x4*)(OP + ((buf * 8 + w) * 64 + mt * 16 + fr) * 16 + fq * 4) = op[mt];
;                 f32x4 u0 = (f32x4){0.f, 0.f, 0.f, 0.f}, u1 = u0;
; #pragma unroll
;                 for (int ks = 0; ks < 2; ++ks) { u0 = mfma16(x.kf[0][ks], x.vf[ks], u0); u1 = mfma16(x.kf[1][ks], x.vf[ks], u1); }
;                 s0 = s0 * x.g0 + u0; s1 = s1 * x.g1 + u1;
;                 asm volatile("s_waitcnt lgkmcnt(0)" ::: "memory"); __builtin_amdgcn_s_barrier(); asm volatile("" ::: "memory");
;                 { const int e = tid * 2; float a = 0.f, b = 0.f;
; #pragma unroll
;                     for (int ww = 0; ww < 8; ++ww) { const f32x2 xx = *(const LAS f32x2*)(OP + (buf * 8 + ww) * 1024 + e); a += xx[0]; b += xx[1]; }
;                     *(unsigned*)(O + ((size_t)(h * 32 + (dv0 >> 4)) * SEQ + t0) * 16 + e) = pk2(a, b); }
.LBB0_1849:
	s_nop 1
	ds_write_b128 v215, v[160:163] offset:32768
	ds_write_b128 v215, v[156:159] offset:33792
	ds_write_b128 v215, v[116:119] offset:34816
	ds_write_b128 v215, v[120:123] offset:35840
	s_waitcnt lgkmcnt(0)
	s_barrier
	v_mfma_f32_16x16x32_bf16 v[132:135], v[132:135], v[148:151], 0
	ds_read2st64_b64 v[120:123], v213 offset0:64 offset1:72
	s_waitcnt lgkmcnt(0)
	v_pk_add_f32 v[82:83], v[120:121], 0 op_sel_hi:[1,0]
	v_mfma_f32_16x16x32_bf16 v[116:119], v[136:139], v[148:151], 0
	v_add_f32_e64 v82, v82, v122
	v_add_f32_e64 v83, v83, v123
	v_mfma_f32_16x16x32_bf16 v[124:127], v[124:127], v[144:147], v[132:135]
	s_nop 2
	ds_read2st64_b64 v[132:135], v213 offset0:80 offset1:88
	ds_read2st64_b64 v[136:139], v213 offset0:96 offset1:104
	ds_read2st64_b64 v[148:151], v213 offset0:112 offset1:120
	s_waitcnt lgkmcnt(2)
	v_pk_add_f32 v[82:83], v[82:83], v[132:133]
	s_nop 0
	v_pk_add_f32 v[82:83], v[82:83], v[134:135]
	v_mfma_f32_16x16x32_bf16 v[116:119], v[128:131], v[144:147], v[116:119]
	s_waitcnt lgkmcnt(1)
	v_pk_add_f32 v[82:83], v[82:83], v[136:137]
	v_pk_fma_f32 v[110:111], v[154:155], v[110:111], v[126:127]
	v_pk_add_f32 v[82:83], v[82:83], v[138:139]
	v_pk_fma_f32 v[108:109], v[152:153], v[108:109], v[124:125]
	s_waitcnt lgkmcnt(0)
	v_pk_add_f32 v[82:83], v[82:83], v[148:149]
	s_nop 0
	v_pk_fma_f32 v[112:113], v[140:141], v[112:113], v[116:117]
	v_pk_add_f32 v[82:83], v[82:83], v[150:151]
	v_pk_fma_f32 v[114:115], v[142:143], v[114:115], v[118:119]
	v_and_b32_sdwa v116, v82, v243 dst_sel:DWORD dst_unused:UNUSED_PAD src0_sel:WORD_1 src1_sel:DWORD
	v_and_b32_sdwa v81, v83, v243 dst_sel:DWORD dst_unused:UNUSED_PAD src0_sel:WORD_1 src1_sel:DWORD
	v_add3_u32 v82, v82, v116, s40
	v_add3_u32 v81, v83, v81, s40
	v_lshrrev_b32_e32 v82, 16, v82
	v_and_or_b32 v81, v81, s41, v82
	v_add_co_u32_e32 v82, vcc, 0xac05000, v240
	s_nop 1
	v_addc_co_u32_e32 v83, vcc, 0, v241, vcc
	global_store_dword v[82:83], v81, off offset:2048 nt
	s_branch .LBB0_1737
